# P8 loop: per-segment s_setprio flips removed, one static s_setprio 1 for waves 0-3 (older half) before the tile loop
# speedup vs baseline: 1.0091x; 1.0091x over previous
.LBB0_1093:
	s_lshl_b32 s4, s4, 5
	s_and_b32 s10, s4, 0x60
	s_lshl_b32 s6, s55, 13
	s_lshl_b32 s7, s10, 7
	s_add_u32 s22, s18, 0xa5b8000
	s_addc_u32 s23, s19, 0
	s_add_u32 s24, s18, 0x15b38000
	s_addc_u32 s25, s19, 0
	s_add_u32 s26, s18, 0x17138000
	s_addc_u32 s27, s19, 0
	s_add_u32 s28, s18, 0x18738000
	s_addc_u32 s29, s19, 0
	s_ashr_i32 s63, s33, 31
	s_add_u32 s30, s12, 0xb000
	s_addc_u32 s31, s13, 0
	s_add_u32 s34, s12, 0x16000
	s_mov_b64 s[36:37], 0x80
	s_addc_u32 s35, s13, 0
	s_add_i32 m0, s21, 0x18000
	v_lshl_add_u64 v[8:9], v[8:9], 0, s[36:37]
	s_waitcnt vmcnt(4)
	s_barrier
	global_load_lds_dwordx4 v[8:9], off
	v_lshl_add_u64 v[6:7], v[6:7], 0, s[36:37]
	s_add_i32 m0, s21, 0x1a000
	s_add_i32 s64, s21, 0x8000
	s_add_i32 s65, s21, 0xa000
	global_load_lds_dwordx4 v[6:7], off
	v_lshl_add_u64 v[4:5], v[4:5], 0, s[36:37]
	s_mov_b32 m0, s64
	s_add_u32 s4, s50, 0x80080
	global_load_lds_dwordx4 v[4:5], off
	v_lshl_add_u64 v[2:3], v[2:3], 0, s[36:37]
	s_mov_b32 m0, s65
	s_addc_u32 s5, s51, 0
	global_load_lds_dwordx4 v[2:3], off
	s_add_i32 m0, s21, 0x1c000
	v_lshl_add_u64 v[2:3], s[4:5], 0, v[162:163]
	global_load_lds_dwordx4 v[2:3], off
	v_lshl_add_u64 v[2:3], s[4:5], 0, v[164:165]
	s_add_i32 m0, s21, 0x1e000
	v_lshlrev_b32_e32 v4, 6, v10
	global_load_lds_dwordx4 v[2:3], off
	v_bfe_u32 v2, v10, 4, 2
	v_lshlrev_b32_e32 v3, 4, v2
	s_movk_i32 s4, 0x3c0
	v_lshlrev_b32_e32 v5, 2, v10
	v_and_or_b32 v4, v4, s4, v3
	v_and_b32_e32 v5, 32, v5
	v_lshl_or_b32 v239, v2, 2, s10
	v_lshlrev_b32_e32 v2, 9, v10
	v_bitop3_b32 v236, s7, v4, v5 bitop3:0xf6
	v_and_b32_e32 v2, 0x70000, v2
	v_lshlrev_b32_e32 v4, 12, v13
	v_or3_b32 v2, v11, v2, v4
	v_and_b32_e32 v1, 15, v10
	v_add_u32_e32 v166, v2, v12
	v_lshlrev_b32_e32 v2, 5, v14
	v_lshl_or_b32 v3, v1, 6, v3
	s_waitcnt vmcnt(6)
	v_and_b32_e32 v2, 0xf0000, v2
	v_lshl_or_b32 v6, s55, 6, v1
	v_bitop3_b32 v3, v3, s6, v5 bitop3:0xde
	v_or3_b32 v2, v11, v2, v4
	s_add_i32 s68, 0, 0x10000
	s_add_i32 s69, 0, 0x14000
	v_cmp_gt_u32_e64 s[4:5], 2, v1
	v_cmp_lt_u32_e64 s[6:7], 13, v1
	v_add_u32_e32 v237, -14, v1
	v_cmp_lt_u32_e64 s[8:9], 1, v1
	v_add_u32_e32 v238, 0xffffc000, v6
	s_ashr_i32 s66, s3, 31
	v_mov_b32_e32 v167, v163
	v_add_u32_e32 v170, v2, v12
	v_mov_b32_e32 v171, v163
	v_mov_b64_e32 v[172:173], 0xbb0
	v_mov_b64_e32 v[174:175], 0xbaf
	s_movk_i32 s67, 0x16c
	s_mov_b32 s87, 28
	v_and_b32_e32 v245, 31, v0
	v_lshlrev_b32_e32 v245, 4, v245
	v_bfe_u32 v250, v0, 5, 1
	v_mul_u32_u24_e32 v250, 0x5800, v250
	v_add_u32_e32 v245, v245, v250
	v_lshlrev_b32_e32 v250, 2, v239
	s_mov_b32 s86, 0x20000
	s_cmpk_lt_u32 s56, 0x1000
	s_cbranch_scc0 .Lp8_prio_done
	s_setprio 1

.Lp8_nostage:
	s_add_u32 s50, s48, 0xfff80080
	s_addc_u32 s51, s49, -1
	s_cmp_eq_u32 s80, s87
	s_cselect_b32 s53, s41, s51
	s_cselect_b32 s52, s47, s50
	s_cselect_b32 s51, s39, s75
	s_cselect_b32 s50, s73, s74
	s_add_i32 m0, s21, 0xc000
	s_nop 0
	global_load_lds_dwordx4 v166, s[48:49]
	s_add_i32 m0, s21, 0xe000
	s_nop 0
	global_load_lds_dwordx4 v170, s[48:49]
	s_waitcnt vmcnt(10)
	s_barrier
	s_waitcnt lgkmcnt(0)
	v_mfma_f32_16x16x32_bf16 v[126:129], v[130:133], v[146:149], 0
	ds_read_b128 v[192:195], v242
	v_mfma_f32_16x16x32_bf16 v[122:125], v[138:141], v[146:149], 0
	v_mfma_f32_16x16x32_bf16 v[118:121], v[130:133], v[154:157], 0
	v_mfma_f32_16x16x32_bf16 v[114:117], v[138:141], v[154:157], 0
	v_mfma_f32_16x16x32_bf16 v[106:109], v[130:133], v[176:179], 0
	ds_read_b128 v[196:199], v242 offset:1024
	v_mfma_f32_16x16x32_bf16 v[98:101], v[138:141], v[176:179], 0
	v_mfma_f32_16x16x32_bf16 v[90:93], v[130:133], v[184:187], 0
	v_mfma_f32_16x16x32_bf16 v[82:85], v[138:141], v[184:187], 0
	v_mfma_f32_16x16x32_bf16 v[126:129], v[134:137], v[150:153], v[126:129]
	ds_read_b128 v[200:203], v242 offset:2048
	v_mfma_f32_16x16x32_bf16 v[122:125], v[142:145], v[150:153], v[122:125]
	v_mfma_f32_16x16x32_bf16 v[118:121], v[134:137], v[158:161], v[118:121]
	v_mfma_f32_16x16x32_bf16 v[114:117], v[142:145], v[158:161], v[114:117]
	v_mfma_f32_16x16x32_bf16 v[106:109], v[134:137], v[180:183], v[106:109]
	ds_read_b128 v[204:207], v242 offset:3072
	v_mfma_f32_16x16x32_bf16 v[98:101], v[142:145], v[180:183], v[98:101]
	v_mfma_f32_16x16x32_bf16 v[90:93], v[134:137], v[188:191], v[90:93]
	v_mfma_f32_16x16x32_bf16 v[82:85], v[142:145], v[188:191], v[82:85]
	s_barrier
	s_add_i32 s81, s68, s56
	s_add_u32 s96, s50, 0x80
	s_addc_u32 s97, s51, 0
	s_mov_b32 m0, s81
	s_nop 0
	global_load_lds_dwordx4 v162, s[50:51]
	s_add_i32 m0, s81, 0x2000
	s_nop 0
	global_load_lds_dwordx4 v164, s[50:51]
	s_waitcnt vmcnt(10)
	s_barrier
	s_waitcnt lgkmcnt(0)
	v_mfma_f32_16x16x32_bf16 v[110:113], v[192:195], v[146:149], 0
	ds_read_b128 v[208:211], v241 offset:16384
	v_mfma_f32_16x16x32_bf16 v[102:105], v[200:203], v[146:149], 0
	v_mfma_f32_16x16x32_bf16 v[94:97], v[192:195], v[154:157], 0
	ds_read_b128 v[212:215], v241 offset:17408
	v_mfma_f32_16x16x32_bf16 v[86:89], v[200:203], v[154:157], 0
	v_mfma_f32_16x16x32_bf16 v[78:81], v[192:195], v[176:179], 0
	ds_read_b128 v[216:219], v241 offset:18432
	v_mfma_f32_16x16x32_bf16 v[74:77], v[200:203], v[176:179], 0
	v_mfma_f32_16x16x32_bf16 v[70:73], v[192:195], v[184:187], 0
	ds_read_b128 v[220:223], v241 offset:19456
	v_mfma_f32_16x16x32_bf16 v[66:69], v[200:203], v[184:187], 0
	v_mfma_f32_16x16x32_bf16 v[110:113], v[196:199], v[150:153], v[110:113]
	ds_read_b128 v[224:227], v241 offset:20480
	v_mfma_f32_16x16x32_bf16 v[102:105], v[204:207], v[150:153], v[102:105]
	v_mfma_f32_16x16x32_bf16 v[94:97], v[196:199], v[158:161], v[94:97]
	ds_read_b128 v[228:231], v241 offset:21504
	v_mfma_f32_16x16x32_bf16 v[86:89], v[204:207], v[158:161], v[86:89]
	v_mfma_f32_16x16x32_bf16 v[78:81], v[196:199], v[180:183], v[78:81]
	ds_read_b128 v[232:235], v241 offset:22528
	v_mfma_f32_16x16x32_bf16 v[74:77], v[204:207], v[180:183], v[74:77]
	v_mfma_f32_16x16x32_bf16 v[70:73], v[196:199], v[188:191], v[70:73]
	ds_read_b128 v[246:249], v241 offset:23552
	v_mfma_f32_16x16x32_bf16 v[66:69], v[204:207], v[188:191], v[66:69]
	s_barrier
	s_mov_b32 m0, s21
	s_add_u32 s94, s52, 0x80
	s_addc_u32 s95, s53, 0
	global_load_lds_dwordx4 v162, s[52:53]
	s_mov_b32 m0, s59
	s_nop 0
	global_load_lds_dwordx4 v164, s[52:53]
	s_waitcnt vmcnt(8)
	s_barrier
	s_waitcnt lgkmcnt(0)
	v_mfma_f32_16x16x32_bf16 v[62:65], v[130:133], v[208:211], 0
	ds_read_b128 v[146:149], v241 offset:32768
	v_mfma_f32_16x16x32_bf16 v[58:61], v[138:141], v[208:211], 0
	v_mfma_f32_16x16x32_bf16 v[54:57], v[130:133], v[216:219], 0
	ds_read_b128 v[150:153], v241 offset:33792
	v_mfma_f32_16x16x32_bf16 v[50:53], v[138:141], v[216:219], 0
	v_mfma_f32_16x16x32_bf16 v[42:45], v[130:133], v[224:227], 0
	ds_read_b128 v[154:157], v241 offset:34816
	v_mfma_f32_16x16x32_bf16 v[34:37], v[138:141], v[224:227], 0
	v_mfma_f32_16x16x32_bf16 v[26:29], v[130:133], v[232:235], 0
	ds_read_b128 v[158:161], v241 offset:35840
	v_mfma_f32_16x16x32_bf16 v[18:21], v[138:141], v[232:235], 0
	v_mfma_f32_16x16x32_bf16 v[62:65], v[134:137], v[212:215], v[62:65]
	ds_read_b128 v[176:179], v241 offset:36864
	v_mfma_f32_16x16x32_bf16 v[58:61], v[142:145], v[212:215], v[58:61]
	v_mfma_f32_16x16x32_bf16 v[54:57], v[134:137], v[220:223], v[54:57]
	ds_read_b128 v[180:183], v241 offset:37888
	v_mfma_f32_16x16x32_bf16 v[50:53], v[142:145], v[220:223], v[50:53]
	v_mfma_f32_16x16x32_bf16 v[42:45], v[134:137], v[228:231], v[42:45]
	ds_read_b128 v[184:187], v241 offset:38912
	v_mfma_f32_16x16x32_bf16 v[34:37], v[142:145], v[228:231], v[34:37]
	v_mfma_f32_16x16x32_bf16 v[26:29], v[134:137], v[246:249], v[26:29]
	ds_read_b128 v[188:191], v241 offset:39936
	v_mfma_f32_16x16x32_bf16 v[18:21], v[142:145], v[246:249], v[18:21]
	s_barrier
	s_add_u32 s82, s50, 0x80000
	s_addc_u32 s83, s51, 0
	s_add_i32 s81, s69, s56
	s_mov_b32 m0, s81
	s_nop 0
	global_load_lds_dwordx4 v162, s[82:83]
	s_add_i32 m0, s81, 0x2000
	s_nop 0
	global_load_lds_dwordx4 v164, s[82:83]
	s_waitcnt vmcnt(10)
	s_barrier
	s_waitcnt lgkmcnt(0)
	v_mfma_f32_16x16x32_bf16 v[46:49], v[192:195], v[208:211], 0
	ds_read_b128 v[130:133], v168
	v_mfma_f32_16x16x32_bf16 v[38:41], v[200:203], v[208:211], 0
	v_mfma_f32_16x16x32_bf16 v[30:33], v[192:195], v[216:219], 0
	v_mfma_f32_16x16x32_bf16 v[22:25], v[200:203], v[216:219], 0
	v_mfma_f32_16x16x32_bf16 v[14:17], v[192:195], v[224:227], 0
	ds_read_b128 v[134:137], v168 offset:1024
	v_mfma_f32_16x16x32_bf16 v[10:13], v[200:203], v[224:227], 0
	v_mfma_f32_16x16x32_bf16 v[6:9], v[192:195], v[232:235], 0
	v_mfma_f32_16x16x32_bf16 v[2:5], v[200:203], v[232:235], 0
	v_mfma_f32_16x16x32_bf16 v[46:49], v[196:199], v[212:215], v[46:49]
	ds_read_b128 v[138:141], v168 offset:2048
	v_mfma_f32_16x16x32_bf16 v[38:41], v[204:207], v[212:215], v[38:41]
	v_mfma_f32_16x16x32_bf16 v[30:33], v[196:199], v[220:223], v[30:33]
	v_mfma_f32_16x16x32_bf16 v[22:25], v[204:207], v[220:223], v[22:25]
	v_mfma_f32_16x16x32_bf16 v[14:17], v[196:199], v[228:231], v[14:17]
	ds_read_b128 v[142:145], v168 offset:3072
	v_mfma_f32_16x16x32_bf16 v[10:13], v[204:207], v[228:231], v[10:13]
	v_mfma_f32_16x16x32_bf16 v[6:9], v[196:199], v[246:249], v[6:9]
	v_mfma_f32_16x16x32_bf16 v[2:5], v[204:207], v[246:249], v[2:5]
	s_barrier
	s_add_i32 s81, 0, 0x18000
	s_add_u32 s52, s52, 0x80000
	s_addc_u32 s53, s53, 0
	s_mov_b32 m0, s60
	s_nop 0
	global_load_lds_dwordx4 v162, s[52:53]
	s_mov_b32 m0, s61
	s_nop 0
	global_load_lds_dwordx4 v164, s[52:53]
	s_waitcnt vmcnt(10)
	s_barrier
	s_waitcnt lgkmcnt(0)
	v_mfma_f32_16x16x32_bf16 v[126:129], v[130:133], v[146:149], v[126:129]
	ds_read_b128 v[192:195], v169
	v_mfma_f32_16x16x32_bf16 v[122:125], v[138:141], v[146:149], v[122:125]
	v_mfma_f32_16x16x32_bf16 v[118:121], v[130:133], v[154:157], v[118:121]
	v_mfma_f32_16x16x32_bf16 v[114:117], v[138:141], v[154:157], v[114:117]
	v_mfma_f32_16x16x32_bf16 v[106:109], v[130:133], v[176:179], v[106:109]
	ds_read_b128 v[196:199], v169 offset:1024
	v_mfma_f32_16x16x32_bf16 v[98:101], v[138:141], v[176:179], v[98:101]
	v_mfma_f32_16x16x32_bf16 v[90:93], v[130:133], v[184:187], v[90:93]
	v_mfma_f32_16x16x32_bf16 v[82:85], v[138:141], v[184:187], v[82:85]
	v_mfma_f32_16x16x32_bf16 v[126:129], v[134:137], v[150:153], v[126:129]
	ds_read_b128 v[200:203], v169 offset:2048
	v_mfma_f32_16x16x32_bf16 v[122:125], v[142:145], v[150:153], v[122:125]
	v_mfma_f32_16x16x32_bf16 v[118:121], v[134:137], v[158:161], v[118:121]
	v_mfma_f32_16x16x32_bf16 v[114:117], v[142:145], v[158:161], v[114:117]
	v_mfma_f32_16x16x32_bf16 v[106:109], v[134:137], v[180:183], v[106:109]
	ds_read_b128 v[204:207], v169 offset:3072
	v_mfma_f32_16x16x32_bf16 v[98:101], v[142:145], v[180:183], v[98:101]
	v_mfma_f32_16x16x32_bf16 v[90:93], v[134:137], v[188:191], v[90:93]
	v_mfma_f32_16x16x32_bf16 v[82:85], v[142:145], v[188:191], v[82:85]
	s_barrier
	s_add_i32 s52, 0, 0x1c000
	s_add_i32 s53, s81, s56
	s_mov_b32 m0, s53
	s_nop 0
	global_load_lds_dwordx4 v162, s[96:97]
	s_add_i32 m0, s53, 0x2000
	s_nop 0
	global_load_lds_dwordx4 v164, s[96:97]
	s_waitcnt vmcnt(10)
	s_barrier
	s_waitcnt lgkmcnt(0)
	v_mfma_f32_16x16x32_bf16 v[110:113], v[192:195], v[146:149], v[110:113]
	ds_read_b128 v[208:211], v241 offset:49152
	v_mfma_f32_16x16x32_bf16 v[102:105], v[200:203], v[146:149], v[102:105]
	v_mfma_f32_16x16x32_bf16 v[94:97], v[192:195], v[154:157], v[94:97]
	ds_read_b128 v[212:215], v241 offset:50176
	v_mfma_f32_16x16x32_bf16 v[86:89], v[200:203], v[154:157], v[86:89]
	v_mfma_f32_16x16x32_bf16 v[78:81], v[192:195], v[176:179], v[78:81]
	ds_read_b128 v[216:219], v241 offset:51200
	v_mfma_f32_16x16x32_bf16 v[74:77], v[200:203], v[176:179], v[74:77]
	v_mfma_f32_16x16x32_bf16 v[70:73], v[192:195], v[184:187], v[70:73]
	ds_read_b128 v[220:223], v241 offset:52224
	v_mfma_f32_16x16x32_bf16 v[66:69], v[200:203], v[184:187], v[66:69]
	v_mfma_f32_16x16x32_bf16 v[110:113], v[196:199], v[150:153], v[110:113]
	ds_read_b128 v[224:227], v241 offset:53248
	v_mfma_f32_16x16x32_bf16 v[102:105], v[204:207], v[150:153], v[102:105]
	v_mfma_f32_16x16x32_bf16 v[94:97], v[196:199], v[158:161], v[94:97]
	ds_read_b128 v[228:231], v241 offset:54272
	v_mfma_f32_16x16x32_bf16 v[86:89], v[204:207], v[158:161], v[86:89]
	v_mfma_f32_16x16x32_bf16 v[78:81], v[196:199], v[180:183], v[78:81]
	ds_read_b128 v[232:235], v241 offset:55296
	v_mfma_f32_16x16x32_bf16 v[74:77], v[204:207], v[180:183], v[74:77]
	v_mfma_f32_16x16x32_bf16 v[70:73], v[196:199], v[188:191], v[70:73]
	ds_read_b128 v[246:249], v241 offset:56320
	v_mfma_f32_16x16x32_bf16 v[66:69], v[204:207], v[188:191], v[66:69]
	s_barrier
	s_mov_b32 m0, s64
	s_nop 0
	global_load_lds_dwordx4 v162, s[94:95]
	s_mov_b32 m0, s65
	s_nop 0
	global_load_lds_dwordx4 v164, s[94:95]
	s_waitcnt vmcnt(8)
	s_barrier
	s_waitcnt lgkmcnt(0)
	v_mfma_f32_16x16x32_bf16 v[62:65], v[130:133], v[208:211], v[62:65]
	ds_read_b128 v[146:149], v241
	v_mfma_f32_16x16x32_bf16 v[58:61], v[138:141], v[208:211], v[58:61]
	v_mfma_f32_16x16x32_bf16 v[54:57], v[130:133], v[216:219], v[54:57]
	ds_read_b128 v[150:153], v241 offset:1024
	v_mfma_f32_16x16x32_bf16 v[50:53], v[138:141], v[216:219], v[50:53]
	v_mfma_f32_16x16x32_bf16 v[42:45], v[130:133], v[224:227], v[42:45]
	ds_read_b128 v[154:157], v241 offset:2048
	v_mfma_f32_16x16x32_bf16 v[34:37], v[138:141], v[224:227], v[34:37]
	v_mfma_f32_16x16x32_bf16 v[26:29], v[130:133], v[232:235], v[26:29]
	ds_read_b128 v[158:161], v241 offset:3072
	v_mfma_f32_16x16x32_bf16 v[18:21], v[138:141], v[232:235], v[18:21]
	v_mfma_f32_16x16x32_bf16 v[62:65], v[134:137], v[212:215], v[62:65]
	ds_read_b128 v[176:179], v241 offset:4096
	v_mfma_f32_16x16x32_bf16 v[58:61], v[142:145], v[212:215], v[58:61]
	v_mfma_f32_16x16x32_bf16 v[54:57], v[134:137], v[220:223], v[54:57]
	ds_read_b128 v[180:183], v241 offset:5120
	v_mfma_f32_16x16x32_bf16 v[50:53], v[142:145], v[220:223], v[50:53]
	v_mfma_f32_16x16x32_bf16 v[42:45], v[134:137], v[228:231], v[42:45]
	ds_read_b128 v[184:187], v241 offset:6144
	v_mfma_f32_16x16x32_bf16 v[34:37], v[142:145], v[228:231], v[34:37]
	v_mfma_f32_16x16x32_bf16 v[26:29], v[134:137], v[246:249], v[26:29]
	ds_read_b128 v[188:191], v241 offset:7168
	v_mfma_f32_16x16x32_bf16 v[18:21], v[142:145], v[246:249], v[18:21]
	s_barrier
	s_add_u32 s50, s50, 0x80080
	s_addc_u32 s51, s51, 0
	s_add_i32 s52, s52, s56
	s_mov_b32 m0, s52
	s_nop 0
	global_load_lds_dwordx4 v162, s[50:51]
	s_add_i32 m0, s52, 0x2000
	s_nop 0
	global_load_lds_dwordx4 v164, s[50:51]
	s_waitcnt vmcnt(10)
	s_barrier
	s_waitcnt lgkmcnt(0)
	v_mfma_f32_16x16x32_bf16 v[46:49], v[192:195], v[208:211], v[46:49]
	ds_read_b128 v[130:133], v240
	v_mfma_f32_16x16x32_bf16 v[38:41], v[200:203], v[208:211], v[38:41]
	v_mfma_f32_16x16x32_bf16 v[30:33], v[192:195], v[216:219], v[30:33]
	v_mfma_f32_16x16x32_bf16 v[22:25], v[200:203], v[216:219], v[22:25]
	v_mfma_f32_16x16x32_bf16 v[14:17], v[192:195], v[224:227], v[14:17]
	ds_read_b128 v[134:137], v240 offset:1024
	v_mfma_f32_16x16x32_bf16 v[10:13], v[200:203], v[224:227], v[10:13]
	v_mfma_f32_16x16x32_bf16 v[6:9], v[192:195], v[232:235], v[6:9]
	v_mfma_f32_16x16x32_bf16 v[2:5], v[200:203], v[232:235], v[2:5]
	v_mfma_f32_16x16x32_bf16 v[46:49], v[196:199], v[212:215], v[46:49]
	ds_read_b128 v[138:141], v240 offset:2048
	v_mfma_f32_16x16x32_bf16 v[38:41], v[204:207], v[212:215], v[38:41]
	v_mfma_f32_16x16x32_bf16 v[30:33], v[196:199], v[220:223], v[30:33]
	v_mfma_f32_16x16x32_bf16 v[22:25], v[204:207], v[220:223], v[22:25]
	v_mfma_f32_16x16x32_bf16 v[14:17], v[196:199], v[228:231], v[14:17]
	ds_read_b128 v[142:145], v240 offset:3072
	v_mfma_f32_16x16x32_bf16 v[10:13], v[204:207], v[228:231], v[10:13]
	v_mfma_f32_16x16x32_bf16 v[6:9], v[196:199], v[246:249], v[6:9]
	v_mfma_f32_16x16x32_bf16 v[2:5], v[204:207], v[246:249], v[2:5]
	s_add_i32 s80, s80, 2
	s_add_u32 s48, s48, 0x100
	s_addc_u32 s49, s49, 0
	s_add_u32 s74, s74, 0x100
	s_addc_u32 s75, s75, 0
	s_cmp_gt_u32 s80, s87
	s_barrier
	s_cbranch_scc0 .LBB0_1098
	s_branch .Lp8_loop_exit
